# v16 plus exact vmcnt counts on the loads-issued paths of both phase-H thin GEMM variants (12 and 14 loads per step)
# baseline (speedup 1.0000x reference)
.LBB0_1755:
	s_cmp_lt_u32 s18, 6
	s_cselect_b64 s[10:11], -1, 0
	s_cmp_gt_u32 s18, 5
	s_cselect_b64 s[8:9], -1, 0
	s_and_b64 vcc, exec, s[8:9]
	s_cbranch_vccnz .Lth4_s1skip
	v_lshl_add_u64 v[18:19], v[210:211], 0, s[0:1]
	v_add_co_u32_e32 v18, vcc, 0x1ca00000, v18
	v_lshl_add_u64 v[2:3], v[218:219], 0, s[0:1]
	v_lshl_add_u64 v[4:5], v[216:217], 0, s[0:1]
	v_lshl_add_u64 v[10:11], v[214:215], 0, s[0:1]
	v_lshl_add_u64 v[12:13], v[212:213], 0, s[0:1]
	v_addc_co_u32_e32 v19, vcc, 0, v19, vcc
	global_load_dwordx4 v[6:9], v[2:3], off offset:-512
	s_nop 0
	global_load_dwordx4 v[2:5], v[4:5], off offset:-512
	s_nop 0
	global_load_dwordx4 v[14:17], v[10:11], off offset:-512
	s_nop 0
	global_load_dwordx4 v[10:13], v[12:13], off offset:-512
	s_nop 0
	global_load_dwordx4 v[46:49], v[18:19], off offset:1024
	global_load_dwordx4 v[42:45], v[18:19], off offset:1088
	global_load_dwordx4 v[38:41], v[18:19], off offset:1152
	global_load_dwordx4 v[34:37], v[18:19], off offset:1216
	global_load_dwordx4 v[30:33], v[18:19], off offset:1280
	global_load_dwordx4 v[26:29], v[18:19], off offset:1344
	global_load_dwordx4 v[22:25], v[18:19], off offset:1408
	s_nop 0
	global_load_dwordx4 v[18:21], v[18:19], off offset:1472
	s_waitcnt vmcnt(24)
	s_branch .LBB0_1757

.LBB0_1757:
	s_bitcmp1_b32 s18, 0
	s_cselect_b32 s2, 0x8400, 0
	v_add_u32_e32 v0, s2, v239
	ds_read_b128 v[194:197], v0
	ds_read_b128 v[234:237], v0 offset:8448
	s_waitcnt lgkmcnt(1)
	v_mfma_f32_16x16x32_bf16 v[146:149], v[194:197], v[66:69], v[146:149]
	ds_read_b128 v[194:197], v0 offset:16896
	s_waitcnt lgkmcnt(1)
	v_mfma_f32_16x16x32_bf16 v[150:153], v[234:237], v[66:69], v[150:153]
	ds_read_b128 v[234:237], v0 offset:25344
	s_waitcnt lgkmcnt(1)
	v_mfma_f32_16x16x32_bf16 v[158:161], v[194:197], v[66:69], v[158:161]
	ds_read_b128 v[194:197], v0 offset:64
	s_waitcnt lgkmcnt(1)
	v_mfma_f32_16x16x32_bf16 v[154:157], v[234:237], v[66:69], v[154:157]
	ds_read_b128 v[234:237], v0 offset:8512
	s_waitcnt lgkmcnt(1)
	v_mfma_f32_16x16x32_bf16 v[146:149], v[194:197], v[70:73], v[146:149]
	ds_read_b128 v[194:197], v0 offset:16960
	s_waitcnt lgkmcnt(1)
	v_mfma_f32_16x16x32_bf16 v[150:153], v[234:237], v[70:73], v[150:153]
	ds_read_b128 v[234:237], v0 offset:25408
	s_waitcnt lgkmcnt(1)
	v_mfma_f32_16x16x32_bf16 v[158:161], v[194:197], v[70:73], v[158:161]
	ds_read_b128 v[194:197], v0 offset:128
	s_waitcnt lgkmcnt(1)
	v_mfma_f32_16x16x32_bf16 v[154:157], v[234:237], v[70:73], v[154:157]
	ds_read_b128 v[234:237], v0 offset:8576
	s_waitcnt lgkmcnt(1)
	v_mfma_f32_16x16x32_bf16 v[146:149], v[194:197], v[82:85], v[146:149]
	ds_read_b128 v[194:197], v0 offset:17024
	s_waitcnt lgkmcnt(1)
	v_mfma_f32_16x16x32_bf16 v[150:153], v[234:237], v[82:85], v[150:153]
	ds_read_b128 v[234:237], v0 offset:25472
	s_waitcnt lgkmcnt(1)
	v_mfma_f32_16x16x32_bf16 v[158:161], v[194:197], v[82:85], v[158:161]
	ds_read_b128 v[194:197], v0 offset:192
	s_waitcnt lgkmcnt(1)
	v_mfma_f32_16x16x32_bf16 v[154:157], v[234:237], v[82:85], v[154:157]
	ds_read_b128 v[234:237], v0 offset:8640
	s_waitcnt lgkmcnt(1)
	v_mfma_f32_16x16x32_bf16 v[146:149], v[194:197], v[86:89], v[146:149]
	ds_read_b128 v[194:197], v0 offset:17088
	s_waitcnt lgkmcnt(1)
	v_mfma_f32_16x16x32_bf16 v[150:153], v[234:237], v[86:89], v[150:153]
	ds_read_b128 v[234:237], v0 offset:25536
	s_waitcnt lgkmcnt(1)
	v_mfma_f32_16x16x32_bf16 v[158:161], v[194:197], v[86:89], v[158:161]
	ds_read_b128 v[194:197], v0 offset:256
	s_waitcnt lgkmcnt(1)
	v_mfma_f32_16x16x32_bf16 v[154:157], v[234:237], v[86:89], v[154:157]
	ds_read_b128 v[234:237], v0 offset:8704
	s_waitcnt lgkmcnt(1)
	v_mfma_f32_16x16x32_bf16 v[146:149], v[194:197], v[98:101], v[146:149]
	ds_read_b128 v[194:197], v0 offset:17152
	s_waitcnt lgkmcnt(1)
	v_mfma_f32_16x16x32_bf16 v[150:153], v[234:237], v[98:101], v[150:153]
	ds_read_b128 v[234:237], v0 offset:25600
	s_waitcnt lgkmcnt(1)
	v_mfma_f32_16x16x32_bf16 v[158:161], v[194:197], v[98:101], v[158:161]
	ds_read_b128 v[194:197], v0 offset:320
	s_waitcnt lgkmcnt(1)
	v_mfma_f32_16x16x32_bf16 v[154:157], v[234:237], v[98:101], v[154:157]
	ds_read_b128 v[234:237], v0 offset:8768
	s_waitcnt lgkmcnt(1)
	v_mfma_f32_16x16x32_bf16 v[146:149], v[194:197], v[102:105], v[146:149]
	ds_read_b128 v[194:197], v0 offset:17216
	s_waitcnt lgkmcnt(1)
	v_mfma_f32_16x16x32_bf16 v[150:153], v[234:237], v[102:105], v[150:153]
	ds_read_b128 v[234:237], v0 offset:25664
	s_waitcnt lgkmcnt(1)
	v_mfma_f32_16x16x32_bf16 v[158:161], v[194:197], v[102:105], v[158:161]
	ds_read_b128 v[194:197], v0 offset:384
	s_waitcnt lgkmcnt(1)
	v_mfma_f32_16x16x32_bf16 v[154:157], v[234:237], v[102:105], v[154:157]
	ds_read_b128 v[234:237], v0 offset:8832
	s_waitcnt lgkmcnt(1)
	v_mfma_f32_16x16x32_bf16 v[146:149], v[194:197], v[106:109], v[146:149]
	ds_read_b128 v[194:197], v0 offset:17280
	s_waitcnt lgkmcnt(1)
	v_mfma_f32_16x16x32_bf16 v[150:153], v[234:237], v[106:109], v[150:153]
	ds_read_b128 v[234:237], v0 offset:25728
	s_waitcnt lgkmcnt(1)
	v_mfma_f32_16x16x32_bf16 v[158:161], v[194:197], v[106:109], v[158:161]
	s_waitcnt lgkmcnt(0)
	v_mfma_f32_16x16x32_bf16 v[194:197], v[234:237], v[106:109], v[154:157]
	s_nop 2
	ds_read_b128 v[154:157], v0 offset:448
	s_waitcnt lgkmcnt(0)
	v_mfma_f32_16x16x32_bf16 v[146:149], v[154:157], v[110:113], v[146:149]
	ds_read_b128 v[154:157], v0 offset:8896
	s_waitcnt lgkmcnt(0)
	v_mfma_f32_16x16x32_bf16 v[150:153], v[154:157], v[110:113], v[150:153]
	ds_read_b128 v[154:157], v0 offset:17344
	s_waitcnt lgkmcnt(0)
	v_mfma_f32_16x16x32_bf16 v[154:157], v[154:157], v[110:113], v[158:161]
	s_nop 2
	ds_read_b128 v[158:161], v0 offset:25792
	s_waitcnt lgkmcnt(0)
	v_mfma_f32_16x16x32_bf16 v[158:161], v[158:161], v[110:113], v[194:197]
	s_cselect_b32 s3, 0, 0x8400
	s_add_i32 s19, s3, 0
	s_nop 0
	v_add_u32_e32 v197, s19, v179
	v_add_u32_e32 v194, s19, v225
	v_add_u32_e32 v195, s19, v223
	v_add_u32_e32 v196, s19, v221
	s_cmp_lg_u64 s[8:9], 0
	s_cbranch_scc1 .Lth4_w1orig
	s_waitcnt vmcnt(20)
	ds_write_b128 v197, v[54:57]
	ds_write_b128 v196, v[62:65]
	ds_write_b128 v195, v[78:81]
	ds_write_b128 v194, v[94:97]
	s_branch .Lth4_w1join
.Lth4_w1orig:
	s_waitcnt vmcnt(11)
	ds_write_b128 v197, v[54:57]
	s_waitcnt vmcnt(10)
	ds_write_b128 v196, v[62:65]
	s_waitcnt vmcnt(9)
	ds_write_b128 v195, v[78:81]
	s_waitcnt vmcnt(8)
	ds_write_b128 v194, v[94:97]
.Lth4_w1join:
	s_waitcnt lgkmcnt(0)
	s_barrier
	s_cmp_gt_u32 s18, 4
	s_cbranch_scc1 .LBB0_1759
	v_lshl_add_u64 v[50:51], v[218:219], 0, s[0:1]
	v_lshl_add_u64 v[58:59], v[216:217], 0, s[0:1]
	v_lshl_add_u64 v[66:67], v[214:215], 0, s[0:1]
	global_load_dwordx4 v[50:53], v[50:51], off
	s_nop 0
	global_load_dwordx4 v[58:61], v[58:59], off
	v_lshl_add_u64 v[68:69], v[212:213], 0, s[0:1]
	global_load_dwordx4 v[74:77], v[66:67], off
	global_load_dwordx4 v[90:93], v[68:69], off
	v_lshl_add_u64 v[66:67], v[210:211], 0, s[0:1]
	v_add_co_u32_e32 v110, vcc, 0x1ca00000, v66
	s_nop 1
	v_addc_co_u32_e32 v111, vcc, 0, v67, vcc
	global_load_dwordx4 v[66:69], v[110:111], off offset:1536
	global_load_dwordx4 v[70:73], v[110:111], off offset:1600
	global_load_dwordx4 v[82:85], v[110:111], off offset:1664
	global_load_dwordx4 v[86:89], v[110:111], off offset:1728
	global_load_dwordx4 v[98:101], v[110:111], off offset:1792
	global_load_dwordx4 v[102:105], v[110:111], off offset:1856
	global_load_dwordx4 v[106:109], v[110:111], off offset:1920
	s_nop 0
	global_load_dwordx4 v[110:113], v[110:111], off offset:1984

.Lth4_s2go:
	v_add_u32_e32 v198, s3, v239
	ds_read_b128 v[194:197], v198
	ds_read_b128 v[234:237], v198 offset:8448
	s_waitcnt lgkmcnt(1)
	v_mfma_f32_16x16x32_bf16 v[146:149], v[194:197], v[114:117], v[146:149]
	ds_read_b128 v[194:197], v198 offset:16896
	s_waitcnt lgkmcnt(1)
	v_mfma_f32_16x16x32_bf16 v[150:153], v[234:237], v[114:117], v[150:153]
	ds_read_b128 v[234:237], v198 offset:25344
	s_waitcnt lgkmcnt(1)
	v_mfma_f32_16x16x32_bf16 v[154:157], v[194:197], v[114:117], v[154:157]
	ds_read_b128 v[194:197], v198 offset:64
	s_waitcnt lgkmcnt(1)
	v_mfma_f32_16x16x32_bf16 v[158:161], v[234:237], v[114:117], v[158:161]
	ds_read_b128 v[234:237], v198 offset:8512
	s_waitcnt lgkmcnt(1)
	v_mfma_f32_16x16x32_bf16 v[146:149], v[194:197], v[118:121], v[146:149]
	ds_read_b128 v[194:197], v198 offset:16960
	s_waitcnt lgkmcnt(1)
	v_mfma_f32_16x16x32_bf16 v[150:153], v[234:237], v[118:121], v[150:153]
	ds_read_b128 v[234:237], v198 offset:25408
	s_waitcnt lgkmcnt(1)
	v_mfma_f32_16x16x32_bf16 v[154:157], v[194:197], v[118:121], v[154:157]
	ds_read_b128 v[194:197], v198 offset:128
	s_waitcnt lgkmcnt(1)
	v_mfma_f32_16x16x32_bf16 v[158:161], v[234:237], v[118:121], v[158:161]
	ds_read_b128 v[234:237], v198 offset:8576
	s_waitcnt lgkmcnt(1)
	v_mfma_f32_16x16x32_bf16 v[146:149], v[194:197], v[122:125], v[146:149]
	ds_read_b128 v[194:197], v198 offset:17024
	s_waitcnt lgkmcnt(1)
	v_mfma_f32_16x16x32_bf16 v[150:153], v[234:237], v[122:125], v[150:153]
	ds_read_b128 v[234:237], v198 offset:25472
	s_waitcnt lgkmcnt(1)
	v_mfma_f32_16x16x32_bf16 v[154:157], v[194:197], v[122:125], v[154:157]
	ds_read_b128 v[194:197], v198 offset:192
	s_waitcnt lgkmcnt(1)
	v_mfma_f32_16x16x32_bf16 v[158:161], v[234:237], v[122:125], v[158:161]
	ds_read_b128 v[234:237], v198 offset:8640
	s_waitcnt lgkmcnt(1)
	v_mfma_f32_16x16x32_bf16 v[146:149], v[194:197], v[126:129], v[146:149]
	ds_read_b128 v[194:197], v198 offset:17088
	s_waitcnt lgkmcnt(1)
	v_mfma_f32_16x16x32_bf16 v[150:153], v[234:237], v[126:129], v[150:153]
	ds_read_b128 v[234:237], v198 offset:25536
	s_waitcnt lgkmcnt(1)
	v_mfma_f32_16x16x32_bf16 v[154:157], v[194:197], v[126:129], v[154:157]
	ds_read_b128 v[194:197], v198 offset:256
	s_waitcnt lgkmcnt(1)
	v_mfma_f32_16x16x32_bf16 v[158:161], v[234:237], v[126:129], v[158:161]
	ds_read_b128 v[234:237], v198 offset:8704
	s_waitcnt lgkmcnt(1)
	v_mfma_f32_16x16x32_bf16 v[146:149], v[194:197], v[130:133], v[146:149]
	ds_read_b128 v[194:197], v198 offset:17152
	s_waitcnt lgkmcnt(1)
	v_mfma_f32_16x16x32_bf16 v[150:153], v[234:237], v[130:133], v[150:153]
	ds_read_b128 v[234:237], v198 offset:25600
	s_waitcnt lgkmcnt(1)
	v_mfma_f32_16x16x32_bf16 v[154:157], v[194:197], v[130:133], v[154:157]
	ds_read_b128 v[194:197], v198 offset:320
	s_waitcnt lgkmcnt(1)
	v_mfma_f32_16x16x32_bf16 v[158:161], v[234:237], v[130:133], v[158:161]
	ds_read_b128 v[234:237], v198 offset:8768
	s_waitcnt lgkmcnt(1)
	v_mfma_f32_16x16x32_bf16 v[146:149], v[194:197], v[134:137], v[146:149]
	ds_read_b128 v[194:197], v198 offset:17216
	s_waitcnt lgkmcnt(1)
	v_mfma_f32_16x16x32_bf16 v[150:153], v[234:237], v[134:137], v[150:153]
	ds_read_b128 v[234:237], v198 offset:25664
	s_waitcnt lgkmcnt(1)
	v_mfma_f32_16x16x32_bf16 v[154:157], v[194:197], v[134:137], v[154:157]
	ds_read_b128 v[194:197], v198 offset:384
	s_waitcnt lgkmcnt(1)
	v_mfma_f32_16x16x32_bf16 v[158:161], v[234:237], v[134:137], v[158:161]
	ds_read_b128 v[234:237], v198 offset:8832
	s_waitcnt lgkmcnt(1)
	v_mfma_f32_16x16x32_bf16 v[146:149], v[194:197], v[138:141], v[146:149]
	ds_read_b128 v[194:197], v198 offset:17280
	s_waitcnt lgkmcnt(1)
	v_mfma_f32_16x16x32_bf16 v[150:153], v[234:237], v[138:141], v[150:153]
	ds_read_b128 v[234:237], v198 offset:25728
	s_waitcnt lgkmcnt(1)
	v_mfma_f32_16x16x32_bf16 v[154:157], v[194:197], v[138:141], v[154:157]
	s_waitcnt lgkmcnt(0)
	v_mfma_f32_16x16x32_bf16 v[194:197], v[234:237], v[138:141], v[158:161]
	s_nop 2
	ds_read_b128 v[158:161], v198 offset:448
	s_waitcnt lgkmcnt(0)
	v_mfma_f32_16x16x32_bf16 v[146:149], v[158:161], v[142:145], v[146:149]
	ds_read_b128 v[158:161], v198 offset:8896
	s_waitcnt lgkmcnt(0)
	v_mfma_f32_16x16x32_bf16 v[150:153], v[158:161], v[142:145], v[150:153]
	ds_read_b128 v[158:161], v198 offset:17344
	s_waitcnt lgkmcnt(0)
	v_mfma_f32_16x16x32_bf16 v[158:161], v[158:161], v[142:145], v[154:157]
	s_nop 2
	ds_read_b128 v[154:157], v198 offset:25792
	s_waitcnt lgkmcnt(0)
	v_mfma_f32_16x16x32_bf16 v[154:157], v[154:157], v[142:145], v[194:197]
	s_andn2_b64 vcc, exec, s[10:11]
	s_cbranch_vccnz .LBB0_1761
	s_add_i32 s2, s2, 0
	v_add_u32_e32 v197, s2, v179
	v_add_u32_e32 v194, s2, v225
	v_add_u32_e32 v195, s2, v223
	v_add_u32_e32 v196, s2, v221
	s_waitcnt vmcnt(20)
	ds_write_b128 v197, v[6:9]
	ds_write_b128 v196, v[2:5]
	ds_write_b128 v195, v[14:17]
	ds_write_b128 v194, v[10:13]

.LBB0_1763:
	s_andn2_b64 vcc, exec, s[8:9]
	s_cbranch_vccnz .LBB0_1768
	s_cmp_gt_u32 s18, 3
	s_cbranch_scc1 .Lth4_s3skip
	v_lshl_add_u64 v[114:115], v[210:211], 0, s[0:1]
	v_add_co_u32_e32 v142, vcc, 0x1ca00000, v114
	v_lshl_add_u64 v[54:55], v[218:219], 0, s[0:1]
	v_lshl_add_u64 v[62:63], v[216:217], 0, s[0:1]
	v_lshl_add_u64 v[78:79], v[214:215], 0, s[0:1]
	v_lshl_add_u64 v[94:95], v[212:213], 0, s[0:1]
	v_addc_co_u32_e32 v143, vcc, 0, v115, vcc
	global_load_dwordx4 v[54:57], v[54:55], off offset:512
	s_nop 0
	global_load_dwordx4 v[62:65], v[62:63], off offset:512
	s_nop 0
	global_load_dwordx4 v[78:81], v[78:79], off offset:512
	s_nop 0
	global_load_dwordx4 v[94:97], v[94:95], off offset:512
	s_nop 0
	global_load_dwordx4 v[114:117], v[142:143], off offset:2048
	global_load_dwordx4 v[118:121], v[142:143], off offset:2112
	global_load_dwordx4 v[122:125], v[142:143], off offset:2176
	global_load_dwordx4 v[126:129], v[142:143], off offset:2240
	global_load_dwordx4 v[130:133], v[142:143], off offset:2304
	global_load_dwordx4 v[134:137], v[142:143], off offset:2368
	global_load_dwordx4 v[138:141], v[142:143], off offset:2432
	s_nop 0
	global_load_dwordx4 v[142:145], v[142:143], off offset:2496
	s_waitcnt vmcnt(24)
	s_mov_b32 s100, 1
	s_branch .LBB0_1766

.LBB0_1766:
	ds_read_b128 v[194:197], v0
	ds_read_b128 v[234:237], v0 offset:8448
	s_waitcnt lgkmcnt(1)
	v_mfma_f32_16x16x32_bf16 v[146:149], v[194:197], v[46:49], v[146:149]
	ds_read_b128 v[194:197], v0 offset:16896
	s_waitcnt lgkmcnt(1)
	v_mfma_f32_16x16x32_bf16 v[150:153], v[234:237], v[46:49], v[150:153]
	ds_read_b128 v[234:237], v0 offset:25344
	s_waitcnt lgkmcnt(1)
	v_mfma_f32_16x16x32_bf16 v[158:161], v[194:197], v[46:49], v[158:161]
	ds_read_b128 v[194:197], v0 offset:64
	s_waitcnt lgkmcnt(1)
	v_mfma_f32_16x16x32_bf16 v[154:157], v[234:237], v[46:49], v[154:157]
	ds_read_b128 v[234:237], v0 offset:8512
	s_waitcnt lgkmcnt(1)
	v_mfma_f32_16x16x32_bf16 v[146:149], v[194:197], v[42:45], v[146:149]
	ds_read_b128 v[194:197], v0 offset:16960
	s_waitcnt lgkmcnt(1)
	v_mfma_f32_16x16x32_bf16 v[150:153], v[234:237], v[42:45], v[150:153]
	ds_read_b128 v[234:237], v0 offset:25408
	s_waitcnt lgkmcnt(1)
	v_mfma_f32_16x16x32_bf16 v[158:161], v[194:197], v[42:45], v[158:161]
	ds_read_b128 v[194:197], v0 offset:128
	s_waitcnt lgkmcnt(1)
	v_mfma_f32_16x16x32_bf16 v[154:157], v[234:237], v[42:45], v[154:157]
	ds_read_b128 v[234:237], v0 offset:8576
	s_waitcnt lgkmcnt(1)
	v_mfma_f32_16x16x32_bf16 v[146:149], v[194:197], v[38:41], v[146:149]
	ds_read_b128 v[194:197], v0 offset:17024
	s_waitcnt lgkmcnt(1)
	v_mfma_f32_16x16x32_bf16 v[150:153], v[234:237], v[38:41], v[150:153]
	ds_read_b128 v[234:237], v0 offset:25472
	s_waitcnt lgkmcnt(1)
	v_mfma_f32_16x16x32_bf16 v[158:161], v[194:197], v[38:41], v[158:161]
	ds_read_b128 v[194:197], v0 offset:192
	s_waitcnt lgkmcnt(1)
	v_mfma_f32_16x16x32_bf16 v[154:157], v[234:237], v[38:41], v[154:157]
	ds_read_b128 v[234:237], v0 offset:8640
	s_waitcnt lgkmcnt(1)
	v_mfma_f32_16x16x32_bf16 v[146:149], v[194:197], v[34:37], v[146:149]
	ds_read_b128 v[194:197], v0 offset:17088
	s_waitcnt lgkmcnt(1)
	v_mfma_f32_16x16x32_bf16 v[150:153], v[234:237], v[34:37], v[150:153]
	ds_read_b128 v[234:237], v0 offset:25536
	s_waitcnt lgkmcnt(1)
	v_mfma_f32_16x16x32_bf16 v[158:161], v[194:197], v[34:37], v[158:161]
	ds_read_b128 v[194:197], v0 offset:256
	s_waitcnt lgkmcnt(1)
	v_mfma_f32_16x16x32_bf16 v[154:157], v[234:237], v[34:37], v[154:157]
	ds_read_b128 v[234:237], v0 offset:8704
	s_waitcnt lgkmcnt(1)
	v_mfma_f32_16x16x32_bf16 v[146:149], v[194:197], v[30:33], v[146:149]
	ds_read_b128 v[194:197], v0 offset:17152
	s_waitcnt lgkmcnt(1)
	v_mfma_f32_16x16x32_bf16 v[150:153], v[234:237], v[30:33], v[150:153]
	ds_read_b128 v[234:237], v0 offset:25600
	s_waitcnt lgkmcnt(1)
	v_mfma_f32_16x16x32_bf16 v[158:161], v[194:197], v[30:33], v[158:161]
	ds_read_b128 v[194:197], v0 offset:320
	s_waitcnt lgkmcnt(1)
	v_mfma_f32_16x16x32_bf16 v[154:157], v[234:237], v[30:33], v[154:157]
	ds_read_b128 v[234:237], v0 offset:8768
	s_waitcnt lgkmcnt(1)
	v_mfma_f32_16x16x32_bf16 v[146:149], v[194:197], v[26:29], v[146:149]
	ds_read_b128 v[194:197], v0 offset:17216
	s_waitcnt lgkmcnt(1)
	v_mfma_f32_16x16x32_bf16 v[150:153], v[234:237], v[26:29], v[150:153]
	ds_read_b128 v[234:237], v0 offset:25664
	s_waitcnt lgkmcnt(1)
	v_mfma_f32_16x16x32_bf16 v[158:161], v[194:197], v[26:29], v[158:161]
	ds_read_b128 v[194:197], v0 offset:384
	s_waitcnt lgkmcnt(1)
	v_mfma_f32_16x16x32_bf16 v[154:157], v[234:237], v[26:29], v[154:157]
	ds_read_b128 v[234:237], v0 offset:8832
	s_waitcnt lgkmcnt(1)
	v_mfma_f32_16x16x32_bf16 v[146:149], v[194:197], v[22:25], v[146:149]
	ds_read_b128 v[194:197], v0 offset:17280
	s_waitcnt lgkmcnt(1)
	v_mfma_f32_16x16x32_bf16 v[150:153], v[234:237], v[22:25], v[150:153]
	ds_read_b128 v[234:237], v0 offset:25728
	s_waitcnt lgkmcnt(1)
	v_mfma_f32_16x16x32_bf16 v[158:161], v[194:197], v[22:25], v[158:161]
	ds_read_b128 v[194:197], v0 offset:448
	s_waitcnt lgkmcnt(1)
	v_mfma_f32_16x16x32_bf16 v[154:157], v[234:237], v[22:25], v[154:157]
	ds_read_b128 v[234:237], v0 offset:8896
	s_waitcnt lgkmcnt(1)
	v_mfma_f32_16x16x32_bf16 v[146:149], v[194:197], v[18:21], v[146:149]
	ds_read_b128 v[194:197], v0 offset:17344
	s_waitcnt lgkmcnt(1)
	v_mfma_f32_16x16x32_bf16 v[150:153], v[234:237], v[18:21], v[150:153]
	ds_read_b128 v[234:237], v0 offset:25792
	s_waitcnt lgkmcnt(1)
	v_mfma_f32_16x16x32_bf16 v[158:161], v[194:197], v[18:21], v[158:161]
	s_waitcnt lgkmcnt(0)
	v_mfma_f32_16x16x32_bf16 v[154:157], v[234:237], v[18:21], v[154:157]
	s_add_i32 s18, s18, 3
	s_cmpk_eq_i32 s0, 0xa00
	s_cbranch_scc1 .LBB0_1754
	s_bitcmp1_b32 s18, 0
	s_cselect_b32 s2, 0x8400, 0
	s_add_i32 s2, s2, 0
	v_add_u32_e32 v196, s2, v179
	v_add_u32_e32 v0, s2, v225
	v_add_u32_e32 v194, s2, v223
	v_add_u32_e32 v195, s2, v221
	s_cmp_eq_u32 s100, 1
	s_cbranch_scc1 .Lth4_w3f
	s_waitcnt vmcnt(8)
	s_branch .Lth4_w3j

.Lth4_w3j:
	ds_write_b128 v196, v[50:53]
	ds_write_b128 v195, v[58:61]
	ds_write_b128 v194, v[74:77]
	ds_write_b128 v0, v[90:93]
	s_branch .LBB0_1754

.LBB0_1773:
	s_cmp_lt_u32 s8, 6
	s_cselect_b64 s[6:7], -1, 0
	s_cmp_gt_u32 s8, 5
	s_cselect_b64 s[4:5], -1, 0
	s_and_b64 vcc, exec, s[4:5]
	s_cbranch_vccnz .Lth6_s1skip
	v_lshl_add_u64 v[114:115], v[224:225], 0, s[0:1]
	v_lshl_add_u64 v[116:117], v[222:223], 0, s[0:1]
	global_load_dwordx4 v[150:153], v[114:115], off offset:-512
	global_load_dwordx4 v[146:149], v[116:117], off offset:-512
	v_lshl_add_u64 v[114:115], v[220:221], 0, s[0:1]
	v_lshl_add_u64 v[116:117], v[218:219], 0, s[0:1]
	global_load_dwordx4 v[158:161], v[114:115], off offset:-512
	global_load_dwordx4 v[154:157], v[116:117], off offset:-512
	v_lshl_add_u64 v[114:115], v[216:217], 0, s[0:1]
	v_lshl_add_u64 v[116:117], v[214:215], 0, s[0:1]
	global_load_dwordx4 v[166:169], v[114:115], off offset:-512
	global_load_dwordx4 v[162:165], v[116:117], off offset:-512
	v_lshl_add_u64 v[114:115], v[212:213], 0, s[0:1]
	v_add_co_u32_e32 v114, vcc, 0x1ca00000, v114
	s_nop 1
	v_addc_co_u32_e32 v115, vcc, 0, v115, vcc
	global_load_dwordx4 v[142:145], v[114:115], off offset:1024
	global_load_dwordx4 v[138:141], v[114:115], off offset:1088
	global_load_dwordx4 v[134:137], v[114:115], off offset:1152
	global_load_dwordx4 v[130:133], v[114:115], off offset:1216
	global_load_dwordx4 v[126:129], v[114:115], off offset:1280
	global_load_dwordx4 v[122:125], v[114:115], off offset:1344
	global_load_dwordx4 v[118:121], v[114:115], off offset:1408
	s_nop 0
	global_load_dwordx4 v[114:117], v[114:115], off offset:1472
	s_waitcnt vmcnt(28)
	s_branch .LBB0_1775
.Lth6_s1skip:
	s_waitcnt vmcnt(14)
.LBB0_1775:
	s_bitcmp1_b32 s8, 0
	s_cselect_b32 s9, 0xc600, 0
	v_add_u32_e32 v246, s9, v245
	ds_read_b128 v[194:197], v246
	ds_read_b128 v[234:237], v246 offset:8448
	s_waitcnt lgkmcnt(1)
	v_mfma_f32_16x16x32_bf16 v[186:189], v[194:197], v[26:29], v[186:189]
	ds_read_b128 v[194:197], v246 offset:16896
	s_waitcnt lgkmcnt(1)
	v_mfma_f32_16x16x32_bf16 v[178:181], v[234:237], v[26:29], v[178:181]
	ds_read_b128 v[234:237], v246 offset:25344
	s_waitcnt lgkmcnt(1)
	v_mfma_f32_16x16x32_bf16 v[170:173], v[194:197], v[26:29], v[170:173]
	ds_read_b128 v[194:197], v246 offset:33792
	s_waitcnt lgkmcnt(1)
	v_mfma_f32_16x16x32_bf16 v[190:193], v[234:237], v[26:29], v[190:193]
	ds_read_b128 v[234:237], v246 offset:42240
	s_waitcnt lgkmcnt(1)
	v_mfma_f32_16x16x32_bf16 v[182:185], v[194:197], v[26:29], v[182:185]
	ds_read_b128 v[194:197], v246 offset:64
	s_waitcnt lgkmcnt(1)
	v_mfma_f32_16x16x32_bf16 v[174:177], v[234:237], v[26:29], v[174:177]
	ds_read_b128 v[234:237], v246 offset:8512
	s_waitcnt lgkmcnt(1)
	v_mfma_f32_16x16x32_bf16 v[186:189], v[194:197], v[38:41], v[186:189]
	ds_read_b128 v[194:197], v246 offset:16960
	s_waitcnt lgkmcnt(1)
	v_mfma_f32_16x16x32_bf16 v[178:181], v[234:237], v[38:41], v[178:181]
	ds_read_b128 v[234:237], v246 offset:25408
	s_waitcnt lgkmcnt(1)
	v_mfma_f32_16x16x32_bf16 v[170:173], v[194:197], v[38:41], v[170:173]
	ds_read_b128 v[194:197], v246 offset:33856
	s_waitcnt lgkmcnt(1)
	v_mfma_f32_16x16x32_bf16 v[190:193], v[234:237], v[38:41], v[190:193]
	ds_read_b128 v[234:237], v246 offset:42304
	s_waitcnt lgkmcnt(1)
	v_mfma_f32_16x16x32_bf16 v[182:185], v[194:197], v[38:41], v[182:185]
	ds_read_b128 v[194:197], v246 offset:128
	s_waitcnt lgkmcnt(1)
	v_mfma_f32_16x16x32_bf16 v[174:177], v[234:237], v[38:41], v[174:177]
	ds_read_b128 v[234:237], v246 offset:8576
	s_waitcnt lgkmcnt(1)
	v_mfma_f32_16x16x32_bf16 v[186:189], v[194:197], v[42:45], v[186:189]
	ds_read_b128 v[194:197], v246 offset:17024
	s_waitcnt lgkmcnt(1)
	v_mfma_f32_16x16x32_bf16 v[178:181], v[234:237], v[42:45], v[178:181]
	ds_read_b128 v[234:237], v246 offset:25472
	s_waitcnt lgkmcnt(1)
	v_mfma_f32_16x16x32_bf16 v[170:173], v[194:197], v[42:45], v[170:173]
	ds_read_b128 v[194:197], v246 offset:33920
	s_waitcnt lgkmcnt(1)
	v_mfma_f32_16x16x32_bf16 v[190:193], v[234:237], v[42:45], v[190:193]
	ds_read_b128 v[234:237], v246 offset:42368
	s_waitcnt lgkmcnt(1)
	v_mfma_f32_16x16x32_bf16 v[182:185], v[194:197], v[42:45], v[182:185]
	ds_read_b128 v[194:197], v246 offset:192
	s_waitcnt lgkmcnt(1)
	v_mfma_f32_16x16x32_bf16 v[174:177], v[234:237], v[42:45], v[174:177]
	ds_read_b128 v[234:237], v246 offset:8640
	s_waitcnt lgkmcnt(1)
	v_mfma_f32_16x16x32_bf16 v[186:189], v[194:197], v[46:49], v[186:189]
	ds_read_b128 v[194:197], v246 offset:17088
	s_waitcnt lgkmcnt(1)
	v_mfma_f32_16x16x32_bf16 v[178:181], v[234:237], v[46:49], v[178:181]
	ds_read_b128 v[234:237], v246 offset:25536
	s_waitcnt lgkmcnt(1)
	v_mfma_f32_16x16x32_bf16 v[170:173], v[194:197], v[46:49], v[170:173]
	ds_read_b128 v[194:197], v246 offset:33984
	s_waitcnt lgkmcnt(1)
	v_mfma_f32_16x16x32_bf16 v[190:193], v[234:237], v[46:49], v[190:193]
	ds_read_b128 v[234:237], v246 offset:42432
	s_waitcnt lgkmcnt(1)
	v_mfma_f32_16x16x32_bf16 v[182:185], v[194:197], v[46:49], v[182:185]
	ds_read_b128 v[194:197], v246 offset:256
	s_waitcnt lgkmcnt(1)
	v_mfma_f32_16x16x32_bf16 v[174:177], v[234:237], v[46:49], v[174:177]
	ds_read_b128 v[234:237], v246 offset:8704
	s_waitcnt lgkmcnt(1)
	v_mfma_f32_16x16x32_bf16 v[186:189], v[194:197], v[58:61], v[186:189]
	ds_read_b128 v[194:197], v246 offset:17152
	s_waitcnt lgkmcnt(1)
	v_mfma_f32_16x16x32_bf16 v[178:181], v[234:237], v[58:61], v[178:181]
	ds_read_b128 v[234:237], v246 offset:25600
	s_waitcnt lgkmcnt(1)
	v_mfma_f32_16x16x32_bf16 v[170:173], v[194:197], v[58:61], v[170:173]
	ds_read_b128 v[194:197], v246 offset:34048
	s_waitcnt lgkmcnt(1)
	v_mfma_f32_16x16x32_bf16 v[190:193], v[234:237], v[58:61], v[190:193]
	ds_read_b128 v[234:237], v246 offset:42496
	s_waitcnt lgkmcnt(1)
	v_mfma_f32_16x16x32_bf16 v[182:185], v[194:197], v[58:61], v[182:185]
	ds_read_b128 v[194:197], v246 offset:320
	s_waitcnt lgkmcnt(1)
	v_mfma_f32_16x16x32_bf16 v[174:177], v[234:237], v[58:61], v[174:177]
	ds_read_b128 v[234:237], v246 offset:8768
	s_waitcnt lgkmcnt(1)
	v_mfma_f32_16x16x32_bf16 v[186:189], v[194:197], v[62:65], v[186:189]
	ds_read_b128 v[194:197], v246 offset:17216
	s_waitcnt lgkmcnt(1)
	v_mfma_f32_16x16x32_bf16 v[178:181], v[234:237], v[62:65], v[178:181]
	ds_read_b128 v[234:237], v246 offset:25664
	s_waitcnt lgkmcnt(1)
	v_mfma_f32_16x16x32_bf16 v[170:173], v[194:197], v[62:65], v[170:173]
	ds_read_b128 v[194:197], v246 offset:34112
	s_waitcnt lgkmcnt(1)
	v_mfma_f32_16x16x32_bf16 v[190:193], v[234:237], v[62:65], v[190:193]
	ds_read_b128 v[234:237], v246 offset:42560
	s_waitcnt lgkmcnt(1)
	v_mfma_f32_16x16x32_bf16 v[182:185], v[194:197], v[62:65], v[182:185]
	ds_read_b128 v[194:197], v246 offset:384
	s_waitcnt lgkmcnt(1)
	v_mfma_f32_16x16x32_bf16 v[174:177], v[234:237], v[62:65], v[174:177]
	ds_read_b128 v[234:237], v246 offset:8832
	s_waitcnt lgkmcnt(1)
	v_mfma_f32_16x16x32_bf16 v[186:189], v[194:197], v[74:77], v[186:189]
	ds_read_b128 v[194:197], v246 offset:17280
	s_waitcnt lgkmcnt(1)
	v_mfma_f32_16x16x32_bf16 v[178:181], v[234:237], v[74:77], v[178:181]
	s_waitcnt lgkmcnt(0)
	v_mfma_f32_16x16x32_bf16 v[194:197], v[194:197], v[74:77], v[170:173]
	s_nop 2
	ds_read_b128 v[170:173], v246 offset:25728
	s_waitcnt lgkmcnt(0)
	v_mfma_f32_16x16x32_bf16 v[190:193], v[170:173], v[74:77], v[190:193]
	ds_read_b128 v[170:173], v246 offset:34176
	s_waitcnt lgkmcnt(0)
	v_mfma_f32_16x16x32_bf16 v[198:201], v[170:173], v[74:77], v[182:185]
	ds_read_b128 v[170:173], v246 offset:42624
	s_nop 1
	ds_read_b128 v[182:185], v246 offset:25792
	s_waitcnt lgkmcnt(1)
	v_mfma_f32_16x16x32_bf16 v[202:205], v[170:173], v[74:77], v[174:177]
	ds_read_b128 v[170:173], v246 offset:448
	s_nop 1
	ds_read_b128 v[174:177], v246 offset:8896
	s_waitcnt lgkmcnt(1)
	v_mfma_f32_16x16x32_bf16 v[170:173], v[170:173], v[78:81], v[186:189]
	s_nop 2
	ds_read_b128 v[186:189], v246 offset:34240
	s_waitcnt lgkmcnt(1)
	v_mfma_f32_16x16x32_bf16 v[174:177], v[174:177], v[78:81], v[178:181]
	s_nop 2
	ds_read_b128 v[178:181], v246 offset:17344
	v_mfma_f32_16x16x32_bf16 v[182:185], v[182:185], v[78:81], v[190:193]
	s_nop 2
	ds_read_b128 v[190:193], v246 offset:42688
	s_waitcnt lgkmcnt(1)
	v_mfma_f32_16x16x32_bf16 v[178:181], v[178:181], v[78:81], v[194:197]
	v_mfma_f32_16x16x32_bf16 v[186:189], v[186:189], v[78:81], v[198:201]
	s_waitcnt lgkmcnt(0)
	v_mfma_f32_16x16x32_bf16 v[190:193], v[190:193], v[78:81], v[202:205]
	s_cselect_b32 s2, 0, 0xc600
	s_add_i32 s3, s2, 0
	v_add_u32_e32 v194, s3, v239
	s_cmp_lg_u64 s[4:5], 0
	s_cbranch_scc1 .Lth6_w1orig
	s_waitcnt vmcnt(22)
	ds_write_b128 v194, v[6:9]
	v_add_u32_e32 v194, s3, v240
	ds_write_b128 v194, v[14:17]
	v_add_u32_e32 v194, s3, v241
	ds_write_b128 v194, v[22:25]
	v_add_u32_e32 v194, s3, v242
	ds_write_b128 v194, v[34:37]
	v_add_u32_e32 v194, s3, v243
	ds_write_b128 v194, v[54:57]
	v_add_u32_e32 v194, s3, v244
	ds_write_b128 v194, v[70:73]
	s_branch .Lth6_w1join
.Lth6_w1orig:
	s_waitcnt vmcnt(13)
	ds_write_b128 v194, v[6:9]
	v_add_u32_e32 v194, s3, v240
	s_waitcnt vmcnt(12)
	ds_write_b128 v194, v[14:17]
	v_add_u32_e32 v194, s3, v241
	s_waitcnt vmcnt(11)
	ds_write_b128 v194, v[22:25]
	v_add_u32_e32 v194, s3, v242
	s_waitcnt vmcnt(10)
	ds_write_b128 v194, v[34:37]
	v_add_u32_e32 v194, s3, v243
	s_waitcnt vmcnt(9)
	ds_write_b128 v194, v[54:57]
	v_add_u32_e32 v194, s3, v244
	s_waitcnt vmcnt(8)
	ds_write_b128 v194, v[70:73]
.Lth6_w1join:
	s_waitcnt lgkmcnt(0)
	s_barrier
	s_cmp_gt_u32 s8, 4
	s_cbranch_scc1 .LBB0_1777
	v_lshl_add_u64 v[2:3], v[224:225], 0, s[0:1]
	v_lshl_add_u64 v[10:11], v[222:223], 0, s[0:1]
	v_lshl_add_u64 v[18:19], v[220:221], 0, s[0:1]
	v_lshl_add_u64 v[26:27], v[218:219], 0, s[0:1]
	global_load_dwordx4 v[2:5], v[2:3], off
	s_nop 0
	global_load_dwordx4 v[10:13], v[10:11], off
	s_nop 0
	global_load_dwordx4 v[18:21], v[18:19], off
	s_nop 0
	global_load_dwordx4 v[30:33], v[26:27], off
	v_lshl_add_u64 v[26:27], v[216:217], 0, s[0:1]
	v_lshl_add_u64 v[28:29], v[214:215], 0, s[0:1]
	global_load_dwordx4 v[50:53], v[26:27], off
	global_load_dwordx4 v[66:69], v[28:29], off
	v_lshl_add_u64 v[26:27], v[212:213], 0, s[0:1]
	v_add_co_u32_e32 v78, vcc, 0x1ca00000, v26
	s_nop 1
	v_addc_co_u32_e32 v79, vcc, 0, v27, vcc
	global_load_dwordx4 v[26:29], v[78:79], off offset:1536
	global_load_dwordx4 v[38:41], v[78:79], off offset:1600
	global_load_dwordx4 v[42:45], v[78:79], off offset:1664
	global_load_dwordx4 v[46:49], v[78:79], off offset:1728
	global_load_dwordx4 v[58:61], v[78:79], off offset:1792
	global_load_dwordx4 v[62:65], v[78:79], off offset:1856
	global_load_dwordx4 v[74:77], v[78:79], off offset:1920
	s_nop 0
	global_load_dwordx4 v[78:81], v[78:79], off offset:1984
.LBB0_1777:
	s_cbranch_scc1 .Lth6_s2slow
	s_waitcnt vmcnt(28)
	s_branch .Lth6_s2go

.Lth6_s2go:
	v_add_u32_e32 v206, s2, v245
	ds_read_b128 v[194:197], v206
	ds_read_b128 v[234:237], v206 offset:8448
	s_waitcnt lgkmcnt(1)
	v_mfma_f32_16x16x32_bf16 v[170:173], v[194:197], v[82:85], v[170:173]
	ds_read_b128 v[194:197], v206 offset:16896
	s_waitcnt lgkmcnt(1)
	v_mfma_f32_16x16x32_bf16 v[174:177], v[234:237], v[82:85], v[174:177]
	ds_read_b128 v[234:237], v206 offset:25344
	s_waitcnt lgkmcnt(1)
	v_mfma_f32_16x16x32_bf16 v[178:181], v[194:197], v[82:85], v[178:181]
	ds_read_b128 v[194:197], v206 offset:33792
	s_waitcnt lgkmcnt(1)
	v_mfma_f32_16x16x32_bf16 v[182:185], v[234:237], v[82:85], v[182:185]
	ds_read_b128 v[234:237], v206 offset:42240
	s_waitcnt lgkmcnt(1)
	v_mfma_f32_16x16x32_bf16 v[186:189], v[194:197], v[82:85], v[186:189]
	ds_read_b128 v[194:197], v206 offset:64
	s_waitcnt lgkmcnt(1)
	v_mfma_f32_16x16x32_bf16 v[190:193], v[234:237], v[82:85], v[190:193]
	ds_read_b128 v[234:237], v206 offset:8512
	s_waitcnt lgkmcnt(1)
	v_mfma_f32_16x16x32_bf16 v[170:173], v[194:197], v[86:89], v[170:173]
	ds_read_b128 v[194:197], v206 offset:16960
	s_waitcnt lgkmcnt(1)
	v_mfma_f32_16x16x32_bf16 v[174:177], v[234:237], v[86:89], v[174:177]
	ds_read_b128 v[234:237], v206 offset:25408
	s_waitcnt lgkmcnt(1)
	v_mfma_f32_16x16x32_bf16 v[178:181], v[194:197], v[86:89], v[178:181]
	ds_read_b128 v[194:197], v206 offset:33856
	s_waitcnt lgkmcnt(1)
	v_mfma_f32_16x16x32_bf16 v[182:185], v[234:237], v[86:89], v[182:185]
	ds_read_b128 v[234:237], v206 offset:42304
	s_waitcnt lgkmcnt(1)
	v_mfma_f32_16x16x32_bf16 v[186:189], v[194:197], v[86:89], v[186:189]
	ds_read_b128 v[194:197], v206 offset:128
	s_waitcnt lgkmcnt(1)
	v_mfma_f32_16x16x32_bf16 v[190:193], v[234:237], v[86:89], v[190:193]
	ds_read_b128 v[234:237], v206 offset:8576
	s_waitcnt lgkmcnt(1)
	v_mfma_f32_16x16x32_bf16 v[170:173], v[194:197], v[90:93], v[170:173]
	ds_read_b128 v[194:197], v206 offset:17024
	s_waitcnt lgkmcnt(1)
	v_mfma_f32_16x16x32_bf16 v[174:177], v[234:237], v[90:93], v[174:177]
	ds_read_b128 v[234:237], v206 offset:25472
	s_waitcnt lgkmcnt(1)
	v_mfma_f32_16x16x32_bf16 v[178:181], v[194:197], v[90:93], v[178:181]
	ds_read_b128 v[194:197], v206 offset:33920
	s_waitcnt lgkmcnt(1)
	v_mfma_f32_16x16x32_bf16 v[182:185], v[234:237], v[90:93], v[182:185]
	ds_read_b128 v[234:237], v206 offset:42368
	s_waitcnt lgkmcnt(1)
	v_mfma_f32_16x16x32_bf16 v[186:189], v[194:197], v[90:93], v[186:189]
	ds_read_b128 v[194:197], v206 offset:192
	s_waitcnt lgkmcnt(1)
	v_mfma_f32_16x16x32_bf16 v[190:193], v[234:237], v[90:93], v[190:193]
	ds_read_b128 v[234:237], v206 offset:8640
	s_waitcnt lgkmcnt(1)
	v_mfma_f32_16x16x32_bf16 v[170:173], v[194:197], v[94:97], v[170:173]
	ds_read_b128 v[194:197], v206 offset:17088
	s_waitcnt lgkmcnt(1)
	v_mfma_f32_16x16x32_bf16 v[174:177], v[234:237], v[94:97], v[174:177]
	ds_read_b128 v[234:237], v206 offset:25536
	s_waitcnt lgkmcnt(1)
	v_mfma_f32_16x16x32_bf16 v[178:181], v[194:197], v[94:97], v[178:181]
	ds_read_b128 v[194:197], v206 offset:33984
	s_waitcnt lgkmcnt(1)
	v_mfma_f32_16x16x32_bf16 v[182:185], v[234:237], v[94:97], v[182:185]
	ds_read_b128 v[234:237], v206 offset:42432
	s_waitcnt lgkmcnt(1)
	v_mfma_f32_16x16x32_bf16 v[186:189], v[194:197], v[94:97], v[186:189]
	ds_read_b128 v[194:197], v206 offset:256
	s_waitcnt lgkmcnt(1)
	v_mfma_f32_16x16x32_bf16 v[190:193], v[234:237], v[94:97], v[190:193]
	ds_read_b128 v[234:237], v206 offset:8704
	s_waitcnt lgkmcnt(1)
	v_mfma_f32_16x16x32_bf16 v[170:173], v[194:197], v[98:101], v[170:173]
	ds_read_b128 v[194:197], v206 offset:17152
	s_waitcnt lgkmcnt(1)
	v_mfma_f32_16x16x32_bf16 v[174:177], v[234:237], v[98:101], v[174:177]
	ds_read_b128 v[234:237], v206 offset:25600
	s_waitcnt lgkmcnt(1)
	v_mfma_f32_16x16x32_bf16 v[178:181], v[194:197], v[98:101], v[178:181]
	ds_read_b128 v[194:197], v206 offset:34048
	s_waitcnt lgkmcnt(1)
	v_mfma_f32_16x16x32_bf16 v[182:185], v[234:237], v[98:101], v[182:185]
	ds_read_b128 v[234:237], v206 offset:42496
	s_waitcnt lgkmcnt(1)
	v_mfma_f32_16x16x32_bf16 v[186:189], v[194:197], v[98:101], v[186:189]
	ds_read_b128 v[194:197], v206 offset:320
	s_waitcnt lgkmcnt(1)
	v_mfma_f32_16x16x32_bf16 v[190:193], v[234:237], v[98:101], v[190:193]
	ds_read_b128 v[234:237], v206 offset:8768
	s_waitcnt lgkmcnt(1)
	v_mfma_f32_16x16x32_bf16 v[170:173], v[194:197], v[102:105], v[170:173]
	ds_read_b128 v[194:197], v206 offset:17216
	s_waitcnt lgkmcnt(1)
	v_mfma_f32_16x16x32_bf16 v[174:177], v[234:237], v[102:105], v[174:177]
	ds_read_b128 v[234:237], v206 offset:25664
	s_waitcnt lgkmcnt(1)
	v_mfma_f32_16x16x32_bf16 v[178:181], v[194:197], v[102:105], v[178:181]
	ds_read_b128 v[194:197], v206 offset:34112
	s_waitcnt lgkmcnt(1)
	v_mfma_f32_16x16x32_bf16 v[182:185], v[234:237], v[102:105], v[182:185]
	ds_read_b128 v[234:237], v206 offset:42560
	s_waitcnt lgkmcnt(1)
	v_mfma_f32_16x16x32_bf16 v[186:189], v[194:197], v[102:105], v[186:189]
	ds_read_b128 v[194:197], v206 offset:384
	s_waitcnt lgkmcnt(1)
	v_mfma_f32_16x16x32_bf16 v[190:193], v[234:237], v[102:105], v[190:193]
	ds_read_b128 v[234:237], v206 offset:8832
	s_waitcnt lgkmcnt(1)
	v_mfma_f32_16x16x32_bf16 v[170:173], v[194:197], v[106:109], v[170:173]
	ds_read_b128 v[194:197], v206 offset:17280
	s_waitcnt lgkmcnt(1)
	v_mfma_f32_16x16x32_bf16 v[174:177], v[234:237], v[106:109], v[174:177]
	s_waitcnt lgkmcnt(0)
	v_mfma_f32_16x16x32_bf16 v[194:197], v[194:197], v[106:109], v[178:181]
	s_nop 2
	ds_read_b128 v[178:181], v206 offset:25728
	ds_read_b128 v[234:237], v206 offset:34176
	s_waitcnt lgkmcnt(1)
	v_mfma_f32_16x16x32_bf16 v[182:185], v[178:181], v[106:109], v[182:185]
	ds_read_b128 v[178:181], v206 offset:42624
	s_waitcnt lgkmcnt(1)
	v_mfma_f32_16x16x32_bf16 v[198:201], v[234:237], v[106:109], v[186:189]
	ds_read_b128 v[234:237], v206 offset:448
	s_waitcnt lgkmcnt(1)
	v_mfma_f32_16x16x32_bf16 v[202:205], v[178:181], v[106:109], v[190:193]
	s_waitcnt lgkmcnt(0)
	v_mfma_f32_16x16x32_bf16 v[186:189], v[234:237], v[110:113], v[170:173]
	s_nop 2
	ds_read_b128 v[170:173], v206 offset:8896
	s_waitcnt lgkmcnt(0)
	v_mfma_f32_16x16x32_bf16 v[178:181], v[170:173], v[110:113], v[174:177]
	s_nop 2
	ds_read_b128 v[174:177], v206 offset:25792
	ds_read_b128 v[170:173], v206 offset:17344
	s_waitcnt lgkmcnt(1)
	v_mfma_f32_16x16x32_bf16 v[190:193], v[174:177], v[110:113], v[182:185]
	ds_read_b128 v[174:177], v206 offset:34240
	s_waitcnt lgkmcnt(0)
	v_mfma_f32_16x16x32_bf16 v[182:185], v[174:177], v[110:113], v[198:201]
	ds_read_b128 v[174:177], v206 offset:42688
	v_mfma_f32_16x16x32_bf16 v[170:173], v[170:173], v[110:113], v[194:197]
	s_waitcnt lgkmcnt(0)
	v_mfma_f32_16x16x32_bf16 v[174:177], v[174:177], v[110:113], v[202:205]
	s_andn2_b64 vcc, exec, s[6:7]
	s_cbranch_vccnz .LBB0_1779
	s_add_i32 s2, s9, 0
	v_add_u32_e32 v194, s2, v239
	s_waitcnt vmcnt(22)
	ds_write_b128 v194, v[150:153]
	v_add_u32_e32 v194, s2, v240
	ds_write_b128 v194, v[146:149]
	v_add_u32_e32 v194, s2, v241
	ds_write_b128 v194, v[158:161]
	v_add_u32_e32 v194, s2, v242
	ds_write_b128 v194, v[154:157]
	v_add_u32_e32 v194, s2, v243
	ds_write_b128 v194, v[166:169]
	v_add_u32_e32 v194, s2, v244
	ds_write_b128 v194, v[162:165]

.LBB0_1781:
	s_andn2_b64 vcc, exec, s[4:5]
	s_cbranch_vccnz .LBB0_1786
	s_cmp_gt_u32 s8, 3
	s_cbranch_scc1 .Lth6_s3skip
	v_lshl_add_u64 v[82:83], v[212:213], 0, s[0:1]
	v_add_co_u32_e32 v110, vcc, 0x1ca00000, v82
	v_lshl_add_u64 v[6:7], v[224:225], 0, s[0:1]
	v_lshl_add_u64 v[14:15], v[222:223], 0, s[0:1]
	v_lshl_add_u64 v[22:23], v[220:221], 0, s[0:1]
	v_lshl_add_u64 v[34:35], v[218:219], 0, s[0:1]
	v_lshl_add_u64 v[54:55], v[216:217], 0, s[0:1]
	v_lshl_add_u64 v[70:71], v[214:215], 0, s[0:1]
	v_addc_co_u32_e32 v111, vcc, 0, v83, vcc
	global_load_dwordx4 v[6:9], v[6:7], off offset:512
	s_nop 0
	global_load_dwordx4 v[14:17], v[14:15], off offset:512
	s_nop 0
	global_load_dwordx4 v[22:25], v[22:23], off offset:512
	s_nop 0
	global_load_dwordx4 v[34:37], v[34:35], off offset:512
	s_nop 0
	global_load_dwordx4 v[54:57], v[54:55], off offset:512
	s_nop 0
	global_load_dwordx4 v[70:73], v[70:71], off offset:512
	s_nop 0
	global_load_dwordx4 v[82:85], v[110:111], off offset:2048
	global_load_dwordx4 v[86:89], v[110:111], off offset:2112
	global_load_dwordx4 v[90:93], v[110:111], off offset:2176
	global_load_dwordx4 v[94:97], v[110:111], off offset:2240
	global_load_dwordx4 v[98:101], v[110:111], off offset:2304
	global_load_dwordx4 v[102:105], v[110:111], off offset:2368
	global_load_dwordx4 v[106:109], v[110:111], off offset:2432
	s_nop 0
	global_load_dwordx4 v[110:113], v[110:111], off offset:2496
	s_waitcnt vmcnt(28)
	s_mov_b32 s100, 1
	s_branch .LBB0_1784
.Lth6_s3skip:
	s_waitcnt vmcnt(14)
	s_mov_b32 s100, 0
.LBB0_1784:
	ds_read_b128 v[194:197], v246
	ds_read_b128 v[234:237], v246 offset:8448
	s_waitcnt lgkmcnt(1)
	v_mfma_f32_16x16x32_bf16 v[186:189], v[194:197], v[142:145], v[186:189]
	ds_read_b128 v[194:197], v246 offset:16896
	s_waitcnt lgkmcnt(1)
	v_mfma_f32_16x16x32_bf16 v[178:181], v[234:237], v[142:145], v[178:181]
	ds_read_b128 v[234:237], v246 offset:25344
	s_waitcnt lgkmcnt(1)
	v_mfma_f32_16x16x32_bf16 v[170:173], v[194:197], v[142:145], v[170:173]
	ds_read_b128 v[194:197], v246 offset:33792
	s_waitcnt lgkmcnt(1)
	v_mfma_f32_16x16x32_bf16 v[190:193], v[234:237], v[142:145], v[190:193]
	ds_read_b128 v[234:237], v246 offset:42240
	s_waitcnt lgkmcnt(1)
	v_mfma_f32_16x16x32_bf16 v[182:185], v[194:197], v[142:145], v[182:185]
	ds_read_b128 v[194:197], v246 offset:64
	s_waitcnt lgkmcnt(1)
	v_mfma_f32_16x16x32_bf16 v[174:177], v[234:237], v[142:145], v[174:177]
	ds_read_b128 v[234:237], v246 offset:8512
	s_waitcnt lgkmcnt(1)
	v_mfma_f32_16x16x32_bf16 v[186:189], v[194:197], v[138:141], v[186:189]
	ds_read_b128 v[194:197], v246 offset:16960
	s_waitcnt lgkmcnt(1)
	v_mfma_f32_16x16x32_bf16 v[178:181], v[234:237], v[138:141], v[178:181]
	ds_read_b128 v[234:237], v246 offset:25408
	s_waitcnt lgkmcnt(1)
	v_mfma_f32_16x16x32_bf16 v[170:173], v[194:197], v[138:141], v[170:173]
	ds_read_b128 v[194:197], v246 offset:33856
	s_waitcnt lgkmcnt(1)
	v_mfma_f32_16x16x32_bf16 v[190:193], v[234:237], v[138:141], v[190:193]
	ds_read_b128 v[234:237], v246 offset:42304
	s_waitcnt lgkmcnt(1)
	v_mfma_f32_16x16x32_bf16 v[182:185], v[194:197], v[138:141], v[182:185]
	ds_read_b128 v[194:197], v246 offset:128
	s_waitcnt lgkmcnt(1)
	v_mfma_f32_16x16x32_bf16 v[174:177], v[234:237], v[138:141], v[174:177]
	ds_read_b128 v[234:237], v246 offset:8576
	s_waitcnt lgkmcnt(1)
	v_mfma_f32_16x16x32_bf16 v[186:189], v[194:197], v[134:137], v[186:189]
	ds_read_b128 v[194:197], v246 offset:17024
	s_waitcnt lgkmcnt(1)
	v_mfma_f32_16x16x32_bf16 v[178:181], v[234:237], v[134:137], v[178:181]
	ds_read_b128 v[234:237], v246 offset:25472
	s_waitcnt lgkmcnt(1)
	v_mfma_f32_16x16x32_bf16 v[170:173], v[194:197], v[134:137], v[170:173]
	ds_read_b128 v[194:197], v246 offset:33920
	s_waitcnt lgkmcnt(1)
	v_mfma_f32_16x16x32_bf16 v[190:193], v[234:237], v[134:137], v[190:193]
	ds_read_b128 v[234:237], v246 offset:42368
	s_waitcnt lgkmcnt(1)
	v_mfma_f32_16x16x32_bf16 v[182:185], v[194:197], v[134:137], v[182:185]
	ds_read_b128 v[194:197], v246 offset:192
	s_waitcnt lgkmcnt(1)
	v_mfma_f32_16x16x32_bf16 v[174:177], v[234:237], v[134:137], v[174:177]
	ds_read_b128 v[234:237], v246 offset:8640
	s_waitcnt lgkmcnt(1)
	v_mfma_f32_16x16x32_bf16 v[186:189], v[194:197], v[130:133], v[186:189]
	ds_read_b128 v[194:197], v246 offset:17088
	s_waitcnt lgkmcnt(1)
	v_mfma_f32_16x16x32_bf16 v[178:181], v[234:237], v[130:133], v[178:181]
	ds_read_b128 v[234:237], v246 offset:25536
	s_waitcnt lgkmcnt(1)
	v_mfma_f32_16x16x32_bf16 v[170:173], v[194:197], v[130:133], v[170:173]
	ds_read_b128 v[194:197], v246 offset:33984
	s_waitcnt lgkmcnt(1)
	v_mfma_f32_16x16x32_bf16 v[190:193], v[234:237], v[130:133], v[190:193]
	ds_read_b128 v[234:237], v246 offset:42432
	s_waitcnt lgkmcnt(1)
	v_mfma_f32_16x16x32_bf16 v[182:185], v[194:197], v[130:133], v[182:185]
	ds_read_b128 v[194:197], v246 offset:256
	s_waitcnt lgkmcnt(1)
	v_mfma_f32_16x16x32_bf16 v[174:177], v[234:237], v[130:133], v[174:177]
	ds_read_b128 v[234:237], v246 offset:8704
	s_waitcnt lgkmcnt(1)
	v_mfma_f32_16x16x32_bf16 v[186:189], v[194:197], v[126:129], v[186:189]
	ds_read_b128 v[194:197], v246 offset:17152
	s_waitcnt lgkmcnt(1)
	v_mfma_f32_16x16x32_bf16 v[178:181], v[234:237], v[126:129], v[178:181]
	ds_read_b128 v[234:237], v246 offset:25600
	s_waitcnt lgkmcnt(1)
	v_mfma_f32_16x16x32_bf16 v[170:173], v[194:197], v[126:129], v[170:173]
	ds_read_b128 v[194:197], v246 offset:34048
	s_waitcnt lgkmcnt(1)
	v_mfma_f32_16x16x32_bf16 v[190:193], v[234:237], v[126:129], v[190:193]
	ds_read_b128 v[234:237], v246 offset:42496
	s_waitcnt lgkmcnt(1)
	v_mfma_f32_16x16x32_bf16 v[182:185], v[194:197], v[126:129], v[182:185]
	ds_read_b128 v[194:197], v246 offset:320
	s_waitcnt lgkmcnt(1)
	v_mfma_f32_16x16x32_bf16 v[174:177], v[234:237], v[126:129], v[174:177]
	ds_read_b128 v[234:237], v246 offset:8768
	s_waitcnt lgkmcnt(1)
	v_mfma_f32_16x16x32_bf16 v[186:189], v[194:197], v[122:125], v[186:189]
	ds_read_b128 v[194:197], v246 offset:17216
	s_waitcnt lgkmcnt(1)
	v_mfma_f32_16x16x32_bf16 v[178:181], v[234:237], v[122:125], v[178:181]
	ds_read_b128 v[234:237], v246 offset:25664
	s_waitcnt lgkmcnt(1)
	v_mfma_f32_16x16x32_bf16 v[170:173], v[194:197], v[122:125], v[170:173]
	ds_read_b128 v[194:197], v246 offset:34112
	s_waitcnt lgkmcnt(1)
	v_mfma_f32_16x16x32_bf16 v[190:193], v[234:237], v[122:125], v[190:193]
	ds_read_b128 v[234:237], v246 offset:42560
	s_waitcnt lgkmcnt(1)
	v_mfma_f32_16x16x32_bf16 v[182:185], v[194:197], v[122:125], v[182:185]
	ds_read_b128 v[194:197], v246 offset:384
	s_waitcnt lgkmcnt(1)
	v_mfma_f32_16x16x32_bf16 v[174:177], v[234:237], v[122:125], v[174:177]
	ds_read_b128 v[234:237], v246 offset:8832
	s_waitcnt lgkmcnt(1)
	v_mfma_f32_16x16x32_bf16 v[186:189], v[194:197], v[118:121], v[186:189]
	ds_read_b128 v[194:197], v246 offset:17280
	s_waitcnt lgkmcnt(1)
	v_mfma_f32_16x16x32_bf16 v[178:181], v[234:237], v[118:121], v[178:181]
	ds_read_b128 v[234:237], v246 offset:25728
	s_waitcnt lgkmcnt(1)
	v_mfma_f32_16x16x32_bf16 v[170:173], v[194:197], v[118:121], v[170:173]
	ds_read_b128 v[194:197], v246 offset:34176
	s_waitcnt lgkmcnt(1)
	v_mfma_f32_16x16x32_bf16 v[190:193], v[234:237], v[118:121], v[190:193]
	ds_read_b128 v[234:237], v246 offset:42624
	s_waitcnt lgkmcnt(1)
	v_mfma_f32_16x16x32_bf16 v[182:185], v[194:197], v[118:121], v[182:185]
	ds_read_b128 v[194:197], v246 offset:448
	s_waitcnt lgkmcnt(1)
	v_mfma_f32_16x16x32_bf16 v[174:177], v[234:237], v[118:121], v[174:177]
	ds_read_b128 v[234:237], v246 offset:8896
	s_waitcnt lgkmcnt(1)
	v_mfma_f32_16x16x32_bf16 v[186:189], v[194:197], v[114:117], v[186:189]
	ds_read_b128 v[194:197], v246 offset:17344
	s_waitcnt lgkmcnt(1)
	v_mfma_f32_16x16x32_bf16 v[178:181], v[234:237], v[114:117], v[178:181]
	ds_read_b128 v[234:237], v246 offset:25792
	s_waitcnt lgkmcnt(1)
	v_mfma_f32_16x16x32_bf16 v[170:173], v[194:197], v[114:117], v[170:173]
	ds_read_b128 v[194:197], v246 offset:34240
	s_waitcnt lgkmcnt(1)
	v_mfma_f32_16x16x32_bf16 v[190:193], v[234:237], v[114:117], v[190:193]
	ds_read_b128 v[234:237], v246 offset:42688
	s_waitcnt lgkmcnt(1)
	v_mfma_f32_16x16x32_bf16 v[182:185], v[194:197], v[114:117], v[182:185]
	s_waitcnt lgkmcnt(0)
	v_mfma_f32_16x16x32_bf16 v[174:177], v[234:237], v[114:117], v[174:177]
	s_add_i32 s8, s8, 3
	s_cmpk_eq_i32 s0, 0xa00
	s_cbranch_scc1 .LBB0_1772
	s_bitcmp1_b32 s8, 0
	s_cselect_b32 s2, 0xc600, 0
	s_add_i32 s2, s2, 0
	v_add_u32_e32 v194, s2, v239
	s_cmp_eq_u32 s100, 1
	s_cbranch_scc1 .Lth6_w3f
	s_waitcnt vmcnt(8)
	s_branch .Lth6_w3j
.Lth6_w3f:
	s_waitcnt vmcnt(22)
.Lth6_w3j:
	ds_write_b128 v194, v[2:5]
	v_add_u32_e32 v194, s2, v240
	ds_write_b128 v194, v[10:13]
	v_add_u32_e32 v194, s2, v241
	ds_write_b128 v194, v[18:21]
	v_add_u32_e32 v194, s2, v242
	ds_write_b128 v194, v[30:33]
	v_add_u32_e32 v194, s2, v243
	ds_write_b128 v194, v[50:53]
	v_add_u32_e32 v194, s2, v244
	ds_write_b128 v194, v[66:69]
	s_branch .LBB0_1772
